# prologue row pass: bf16 rows stored as 16-byte write-through stores (neighbour-lane DPP exchange) instead of 8-byte ones
# speedup vs baseline: 1.0001x; 1.0001x over previous
.LBB0_671:
	s_or_b64 exec, exec, s[4:5]
	s_cmpk_gt_i32 s8, 0x3fff
	s_cbranch_scc1 .LBB0_676
	s_ashr_i32 s9, s8, 31
	s_lshl_b64 s[4:5], s[8:9], 11
	s_add_u32 s4, s80, s4
	s_addc_u32 s5, s81, s5
	s_ashr_i32 s7, s6, 31
	s_lshl_b64 s[10:11], s[6:7], 11
	s_lshl_b64 s[12:13], s[8:9], 2
	s_add_u32 s12, s78, s12
	s_addc_u32 s13, s79, s13
	s_lshl_b64 s[14:15], s[6:7], 2
	s_lshl_b64 s[16:17], s[8:9], 12
	v_readlane_b32 s56, v254, 14
	v_lshlrev_b32_e32 v2, 2, v218
	v_readlane_b32 s57, v254, 15
	s_add_u32 s16, s56, s16
	v_xor_b32_e32 v1, 4, v2
	v_xor_b32_e32 v20, 8, v2
	v_xor_b32_e32 v21, 16, v2
	v_xor_b32_e32 v22, 32, v2
	v_xor_b32_e32 v23, 64, v2
	v_xor_b32_e32 v24, 0x80, v2
	v_lshlrev_b32_e32 v2, 4, v218
	s_waitcnt lgkmcnt(0)
	v_mov_b32_e32 v3, v0
	s_addc_u32 s17, s57, s17
	v_lshl_add_u64 v[2:3], s[16:17], 0, v[2:3]
	s_mov_b64 s[16:17], 0xc00
	v_cmp_eq_u32_e32 vcc, 0, v218
	v_lshl_add_u64 v[18:19], v[2:3], 0, s[16:17]
	s_lshl_b64 s[16:17], s[6:7], 12
	v_lshlrev_b32_e32 v25, 3, v218
	s_mov_b32 s7, s8
	v_readlane_b32 s58, v254, 16
	v_readlane_b32 s59, v254, 17
	v_readlane_b32 s60, v254, 18
	v_readlane_b32 s61, v254, 19
	v_readlane_b32 s62, v254, 20
	v_readlane_b32 s63, v254, 21
	v_readlane_b32 s64, v254, 22
	v_readlane_b32 s65, v254, 23
	v_readlane_b32 s66, v254, 24
	v_readlane_b32 s67, v254, 25
	v_readlane_b32 s68, v254, 26
	v_readlane_b32 s69, v254, 27
	v_readlane_b32 s70, v254, 28
	v_readlane_b32 s71, v254, 29
	s_cmpk_lg_i32 s6, 0x800
	s_cbranch_scc1 .LBB0_674
	v_and_b32_e32 v171, 1, v218
	v_lshrrev_b32_e32 v170, 1, v218
	v_cmp_eq_u32_e64 s[100:101], 1, v171
	v_lshlrev_b32_e32 v170, 4, v170
	v_lshl_or_b32 v170, v171, 9, v170
	global_load_dwordx4 v[46:49], v[18:19], off offset:-3072 nt
	global_load_dwordx4 v[42:45], v[18:19], off offset:-2048 nt
	global_load_dwordx4 v[38:41], v[18:19], off offset:-1024 nt
	global_load_dwordx4 v[34:37], v[18:19], off nt
	v_lshl_add_u64 v[18:19], v[18:19], 0, s[16:17]
	global_load_dwordx4 v[62:65], v[18:19], off offset:-3072 nt
	global_load_dwordx4 v[58:61], v[18:19], off offset:-2048 nt
	global_load_dwordx4 v[54:57], v[18:19], off offset:-1024 nt
	global_load_dwordx4 v[50:53], v[18:19], off nt
	v_lshl_add_u64 v[18:19], v[18:19], 0, s[16:17]
	global_load_dwordx4 v[78:81], v[18:19], off offset:-3072 nt
	global_load_dwordx4 v[74:77], v[18:19], off offset:-2048 nt
	global_load_dwordx4 v[70:73], v[18:19], off offset:-1024 nt
	global_load_dwordx4 v[66:69], v[18:19], off nt
	v_lshl_add_u64 v[18:19], v[18:19], 0, s[16:17]
	global_load_dwordx4 v[94:97], v[18:19], off offset:-3072 nt
	global_load_dwordx4 v[90:93], v[18:19], off offset:-2048 nt
	global_load_dwordx4 v[86:89], v[18:19], off offset:-1024 nt
	global_load_dwordx4 v[82:85], v[18:19], off nt
	v_lshl_add_u64 v[18:19], v[18:19], 0, s[16:17]
	global_load_dwordx4 v[110:113], v[18:19], off offset:-3072 nt
	global_load_dwordx4 v[106:109], v[18:19], off offset:-2048 nt
	global_load_dwordx4 v[102:105], v[18:19], off offset:-1024 nt
	global_load_dwordx4 v[98:101], v[18:19], off nt
	v_lshl_add_u64 v[18:19], v[18:19], 0, s[16:17]
	global_load_dwordx4 v[126:129], v[18:19], off offset:-3072 nt
	global_load_dwordx4 v[122:125], v[18:19], off offset:-2048 nt
	global_load_dwordx4 v[118:121], v[18:19], off offset:-1024 nt
	global_load_dwordx4 v[114:117], v[18:19], off nt
	v_lshl_add_u64 v[18:19], v[18:19], 0, s[16:17]
	global_load_dwordx4 v[142:145], v[18:19], off offset:-3072 nt
	global_load_dwordx4 v[138:141], v[18:19], off offset:-2048 nt
	global_load_dwordx4 v[134:137], v[18:19], off offset:-1024 nt
	global_load_dwordx4 v[130:133], v[18:19], off nt
	v_lshl_add_u64 v[18:19], v[18:19], 0, s[16:17]
	global_load_dwordx4 v[158:161], v[18:19], off offset:-3072 nt
	global_load_dwordx4 v[154:157], v[18:19], off offset:-2048 nt
	global_load_dwordx4 v[150:153], v[18:19], off offset:-1024 nt
	global_load_dwordx4 v[146:149], v[18:19], off nt
	s_waitcnt vmcnt(28)
	v_mul_f32_e32 v26, v47, v47
	v_mul_f32_e32 v27, v49, v49
	v_mul_f32_e32 v28, v43, v43
	v_mul_f32_e32 v29, v45, v45
	v_mul_f32_e32 v30, v39, v39
	v_mul_f32_e32 v31, v41, v41
	v_fmac_f32_e32 v26, v46, v46
	v_fmac_f32_e32 v27, v48, v48
	v_fmac_f32_e32 v28, v42, v42
	v_fmac_f32_e32 v29, v44, v44
	v_mul_f32_e32 v32, v35, v35
	v_mul_f32_e32 v33, v37, v37
	v_fmac_f32_e32 v30, v38, v38
	v_fmac_f32_e32 v31, v40, v40
	v_add_f32_e32 v26, v26, v27
	v_add_f32_e32 v27, v28, v29
	v_fmac_f32_e32 v32, v34, v34
	v_fmac_f32_e32 v33, v36, v36
	v_add_f32_e32 v28, v30, v31
	v_add_f32_e32 v26, v26, v27
	v_add_f32_e32 v26, v26, v28
	v_add_f32_e32 v27, v32, v33
	v_add_f32_e32 v26, v26, v27
	ds_bpermute_b32 v27, v1, v26
	s_waitcnt lgkmcnt(0)
	v_add_f32_e32 v26, v26, v27
	ds_bpermute_b32 v27, v20, v26
	s_waitcnt lgkmcnt(0)
	v_add_f32_e32 v26, v26, v27
	ds_bpermute_b32 v27, v21, v26
	s_waitcnt lgkmcnt(0)
	v_add_f32_e32 v26, v26, v27
	ds_bpermute_b32 v27, v22, v26
	s_waitcnt lgkmcnt(0)
	v_add_f32_e32 v26, v26, v27
	ds_bpermute_b32 v27, v23, v26
	s_waitcnt lgkmcnt(0)
	v_add_f32_e32 v26, v26, v27
	ds_bpermute_b32 v27, v24, v26
	v_cvt_pk_bf16_f32 v28, v46, v47
	v_cvt_pk_bf16_f32 v29, v48, v49
	v_cvt_pk_bf16_f32 v30, v42, v43
	v_cvt_pk_bf16_f32 v31, v44, v45
	v_cndmask_b32_e64 v42, v30, v28, s[100:101]
	v_cndmask_b32_e64 v43, v31, v29, s[100:101]
	v_cvt_pk_bf16_f32 v32, v38, v39
	v_cvt_pk_bf16_f32 v33, v40, v41
	v_mov_b32_dpp v44, v42 quad_perm:[1,0,3,2] row_mask:0xf bank_mask:0xf
	v_mov_b32_dpp v45, v43 quad_perm:[1,0,3,2] row_mask:0xf bank_mask:0xf
	v_cndmask_b32_e64 v46, v28, v44, s[100:101]
	v_cndmask_b32_e64 v47, v29, v45, s[100:101]
	v_cndmask_b32_e64 v48, v44, v30, s[100:101]
	v_cndmask_b32_e64 v49, v45, v31, s[100:101]
	global_store_dwordx4 v170, v[46:49], s[4:5] sc1
	v_cvt_pk_bf16_f32 v28, v34, v35
	v_cvt_pk_bf16_f32 v29, v36, v37
	v_cndmask_b32_e64 v34, v28, v32, s[100:101]
	v_cndmask_b32_e64 v35, v29, v33, s[100:101]
	s_nop 1
	v_mov_b32_dpp v36, v34 quad_perm:[1,0,3,2] row_mask:0xf bank_mask:0xf
	v_mov_b32_dpp v37, v35 quad_perm:[1,0,3,2] row_mask:0xf bank_mask:0xf
	v_cndmask_b32_e64 v38, v32, v36, s[100:101]
	v_cndmask_b32_e64 v39, v33, v37, s[100:101]
	v_cndmask_b32_e64 v40, v36, v28, s[100:101]
	v_cndmask_b32_e64 v41, v37, v29, s[100:101]
	global_store_dwordx4 v170, v[38:41], s[4:5] offset:1024 sc1
	s_and_saveexec_b64 s[18:19], vcc
	s_waitcnt lgkmcnt(0)
	v_add_f32_e32 v26, v26, v27
	v_min_f32_e32 v26, 0x49742400, v26
	v_fma_f32 v26, v26, s40, 0.5
	v_cvt_u32_f32_e32 v26, v26
	global_store_dword v0, v26, s[12:13]
	s_or_b64 exec, exec, s[18:19]
	s_add_u32 s4, s4, s10
	s_addc_u32 s5, s5, s11
	s_add_u32 s12, s12, s14
	s_addc_u32 s13, s13, s15
	s_waitcnt vmcnt(27)
	v_mul_f32_e32 v26, v63, v63
	v_mul_f32_e32 v27, v65, v65
	v_mul_f32_e32 v28, v59, v59
	v_mul_f32_e32 v29, v61, v61
	v_mul_f32_e32 v30, v55, v55
	v_mul_f32_e32 v31, v57, v57
	v_fmac_f32_e32 v26, v62, v62
	v_fmac_f32_e32 v27, v64, v64
	v_fmac_f32_e32 v28, v58, v58
	v_fmac_f32_e32 v29, v60, v60
	v_mul_f32_e32 v32, v51, v51
	v_mul_f32_e32 v33, v53, v53
	v_fmac_f32_e32 v30, v54, v54
	v_fmac_f32_e32 v31, v56, v56
	v_add_f32_e32 v26, v26, v27
	v_add_f32_e32 v27, v28, v29
	v_fmac_f32_e32 v32, v50, v50
	v_fmac_f32_e32 v33, v52, v52
	v_add_f32_e32 v28, v30, v31
	v_add_f32_e32 v26, v26, v27
	v_add_f32_e32 v26, v26, v28
	v_add_f32_e32 v27, v32, v33
	v_add_f32_e32 v26, v26, v27
	ds_bpermute_b32 v27, v1, v26
	s_waitcnt lgkmcnt(0)
	v_add_f32_e32 v26, v26, v27
	ds_bpermute_b32 v27, v20, v26
	s_waitcnt lgkmcnt(0)
	v_add_f32_e32 v26, v26, v27
	ds_bpermute_b32 v27, v21, v26
	s_waitcnt lgkmcnt(0)
	v_add_f32_e32 v26, v26, v27
	ds_bpermute_b32 v27, v22, v26
	s_waitcnt lgkmcnt(0)
	v_add_f32_e32 v26, v26, v27
	ds_bpermute_b32 v27, v23, v26
	s_waitcnt lgkmcnt(0)
	v_add_f32_e32 v26, v26, v27
	ds_bpermute_b32 v27, v24, v26
	v_cvt_pk_bf16_f32 v28, v62, v63
	v_cvt_pk_bf16_f32 v29, v64, v65
	v_cvt_pk_bf16_f32 v30, v58, v59
	v_cvt_pk_bf16_f32 v31, v60, v61
	v_cndmask_b32_e64 v58, v30, v28, s[100:101]
	v_cndmask_b32_e64 v59, v31, v29, s[100:101]
	v_cvt_pk_bf16_f32 v32, v54, v55
	v_cvt_pk_bf16_f32 v33, v56, v57
	v_mov_b32_dpp v60, v58 quad_perm:[1,0,3,2] row_mask:0xf bank_mask:0xf
	v_mov_b32_dpp v61, v59 quad_perm:[1,0,3,2] row_mask:0xf bank_mask:0xf
	v_cndmask_b32_e64 v62, v28, v60, s[100:101]
	v_cndmask_b32_e64 v63, v29, v61, s[100:101]
	v_cndmask_b32_e64 v64, v60, v30, s[100:101]
	v_cndmask_b32_e64 v65, v61, v31, s[100:101]
	global_store_dwordx4 v170, v[62:65], s[4:5] sc1
	v_cvt_pk_bf16_f32 v28, v50, v51
	v_cvt_pk_bf16_f32 v29, v52, v53
	v_cndmask_b32_e64 v50, v28, v32, s[100:101]
	v_cndmask_b32_e64 v51, v29, v33, s[100:101]
	s_nop 1
	v_mov_b32_dpp v52, v50 quad_perm:[1,0,3,2] row_mask:0xf bank_mask:0xf
	v_mov_b32_dpp v53, v51 quad_perm:[1,0,3,2] row_mask:0xf bank_mask:0xf
	v_cndmask_b32_e64 v54, v32, v52, s[100:101]
	v_cndmask_b32_e64 v55, v33, v53, s[100:101]
	v_cndmask_b32_e64 v56, v52, v28, s[100:101]
	v_cndmask_b32_e64 v57, v53, v29, s[100:101]
	global_store_dwordx4 v170, v[54:57], s[4:5] offset:1024 sc1
	s_and_saveexec_b64 s[18:19], vcc
	s_waitcnt lgkmcnt(0)
	v_add_f32_e32 v26, v26, v27
	v_min_f32_e32 v26, 0x49742400, v26
	v_fma_f32 v26, v26, s40, 0.5
	v_cvt_u32_f32_e32 v26, v26
	global_store_dword v0, v26, s[12:13]
	s_or_b64 exec, exec, s[18:19]
	s_add_u32 s4, s4, s10
	s_addc_u32 s5, s5, s11
	s_add_u32 s12, s12, s14
	s_addc_u32 s13, s13, s15
	s_waitcnt vmcnt(26)
	v_mul_f32_e32 v26, v79, v79
	v_mul_f32_e32 v27, v81, v81
	v_mul_f32_e32 v28, v75, v75
	v_mul_f32_e32 v29, v77, v77
	v_mul_f32_e32 v30, v71, v71
	v_mul_f32_e32 v31, v73, v73
	v_fmac_f32_e32 v26, v78, v78
	v_fmac_f32_e32 v27, v80, v80
	v_fmac_f32_e32 v28, v74, v74
	v_fmac_f32_e32 v29, v76, v76
	v_mul_f32_e32 v32, v67, v67
	v_mul_f32_e32 v33, v69, v69
	v_fmac_f32_e32 v30, v70, v70
	v_fmac_f32_e32 v31, v72, v72
	v_add_f32_e32 v26, v26, v27
	v_add_f32_e32 v27, v28, v29
	v_fmac_f32_e32 v32, v66, v66
	v_fmac_f32_e32 v33, v68, v68
	v_add_f32_e32 v28, v30, v31
	v_add_f32_e32 v26, v26, v27
	v_add_f32_e32 v26, v26, v28
	v_add_f32_e32 v27, v32, v33
	v_add_f32_e32 v26, v26, v27
	ds_bpermute_b32 v27, v1, v26
	s_waitcnt lgkmcnt(0)
	v_add_f32_e32 v26, v26, v27
	ds_bpermute_b32 v27, v20, v26
	s_waitcnt lgkmcnt(0)
	v_add_f32_e32 v26, v26, v27
	ds_bpermute_b32 v27, v21, v26
	s_waitcnt lgkmcnt(0)
	v_add_f32_e32 v26, v26, v27
	ds_bpermute_b32 v27, v22, v26
	s_waitcnt lgkmcnt(0)
	v_add_f32_e32 v26, v26, v27
	ds_bpermute_b32 v27, v23, v26
	s_waitcnt lgkmcnt(0)
	v_add_f32_e32 v26, v26, v27
	ds_bpermute_b32 v27, v24, v26
	v_cvt_pk_bf16_f32 v28, v78, v79
	v_cvt_pk_bf16_f32 v29, v80, v81
	v_cvt_pk_bf16_f32 v30, v74, v75
	v_cvt_pk_bf16_f32 v31, v76, v77
	v_cndmask_b32_e64 v74, v30, v28, s[100:101]
	v_cndmask_b32_e64 v75, v31, v29, s[100:101]
	v_cvt_pk_bf16_f32 v32, v70, v71
	v_cvt_pk_bf16_f32 v33, v72, v73
	v_mov_b32_dpp v76, v74 quad_perm:[1,0,3,2] row_mask:0xf bank_mask:0xf
	v_mov_b32_dpp v77, v75 quad_perm:[1,0,3,2] row_mask:0xf bank_mask:0xf
	v_cndmask_b32_e64 v78, v28, v76, s[100:101]
	v_cndmask_b32_e64 v79, v29, v77, s[100:101]
	v_cndmask_b32_e64 v80, v76, v30, s[100:101]
	v_cndmask_b32_e64 v81, v77, v31, s[100:101]
	global_store_dwordx4 v170, v[78:81], s[4:5] sc1
	v_cvt_pk_bf16_f32 v28, v66, v67
	v_cvt_pk_bf16_f32 v29, v68, v69
	v_cndmask_b32_e64 v66, v28, v32, s[100:101]
	v_cndmask_b32_e64 v67, v29, v33, s[100:101]
	s_nop 1
	v_mov_b32_dpp v68, v66 quad_perm:[1,0,3,2] row_mask:0xf bank_mask:0xf
	v_mov_b32_dpp v69, v67 quad_perm:[1,0,3,2] row_mask:0xf bank_mask:0xf
	v_cndmask_b32_e64 v70, v32, v68, s[100:101]
	v_cndmask_b32_e64 v71, v33, v69, s[100:101]
	v_cndmask_b32_e64 v72, v68, v28, s[100:101]
	v_cndmask_b32_e64 v73, v69, v29, s[100:101]
	global_store_dwordx4 v170, v[70:73], s[4:5] offset:1024 sc1
	s_and_saveexec_b64 s[18:19], vcc
	s_waitcnt lgkmcnt(0)
	v_add_f32_e32 v26, v26, v27
	v_min_f32_e32 v26, 0x49742400, v26
	v_fma_f32 v26, v26, s40, 0.5
	v_cvt_u32_f32_e32 v26, v26
	global_store_dword v0, v26, s[12:13]
	s_or_b64 exec, exec, s[18:19]
	s_add_u32 s4, s4, s10
	s_addc_u32 s5, s5, s11
	s_add_u32 s12, s12, s14
	s_addc_u32 s13, s13, s15
	s_waitcnt vmcnt(25)
	v_mul_f32_e32 v26, v95, v95
	v_mul_f32_e32 v27, v97, v97
	v_mul_f32_e32 v28, v91, v91
	v_mul_f32_e32 v29, v93, v93
	v_mul_f32_e32 v30, v87, v87
	v_mul_f32_e32 v31, v89, v89
	v_fmac_f32_e32 v26, v94, v94
	v_fmac_f32_e32 v27, v96, v96
	v_fmac_f32_e32 v28, v90, v90
	v_fmac_f32_e32 v29, v92, v92
	v_mul_f32_e32 v32, v83, v83
	v_mul_f32_e32 v33, v85, v85
	v_fmac_f32_e32 v30, v86, v86
	v_fmac_f32_e32 v31, v88, v88
	v_add_f32_e32 v26, v26, v27
	v_add_f32_e32 v27, v28, v29
	v_fmac_f32_e32 v32, v82, v82
	v_fmac_f32_e32 v33, v84, v84
	v_add_f32_e32 v28, v30, v31
	v_add_f32_e32 v26, v26, v27
	v_add_f32_e32 v26, v26, v28
	v_add_f32_e32 v27, v32, v33
	v_add_f32_e32 v26, v26, v27
	ds_bpermute_b32 v27, v1, v26
	s_waitcnt lgkmcnt(0)
	v_add_f32_e32 v26, v26, v27
	ds_bpermute_b32 v27, v20, v26
	s_waitcnt lgkmcnt(0)
	v_add_f32_e32 v26, v26, v27
	ds_bpermute_b32 v27, v21, v26
	s_waitcnt lgkmcnt(0)
	v_add_f32_e32 v26, v26, v27
	ds_bpermute_b32 v27, v22, v26
	s_waitcnt lgkmcnt(0)
	v_add_f32_e32 v26, v26, v27
	ds_bpermute_b32 v27, v23, v26
	s_waitcnt lgkmcnt(0)
	v_add_f32_e32 v26, v26, v27
	ds_bpermute_b32 v27, v24, v26
	v_cvt_pk_bf16_f32 v28, v94, v95
	v_cvt_pk_bf16_f32 v29, v96, v97
	v_cvt_pk_bf16_f32 v30, v90, v91
	v_cvt_pk_bf16_f32 v31, v92, v93
	v_cndmask_b32_e64 v90, v30, v28, s[100:101]
	v_cndmask_b32_e64 v91, v31, v29, s[100:101]
	v_cvt_pk_bf16_f32 v32, v86, v87
	v_cvt_pk_bf16_f32 v33, v88, v89
	v_mov_b32_dpp v92, v90 quad_perm:[1,0,3,2] row_mask:0xf bank_mask:0xf
	v_mov_b32_dpp v93, v91 quad_perm:[1,0,3,2] row_mask:0xf bank_mask:0xf
	v_cndmask_b32_e64 v94, v28, v92, s[100:101]
	v_cndmask_b32_e64 v95, v29, v93, s[100:101]
	v_cndmask_b32_e64 v96, v92, v30, s[100:101]
	v_cndmask_b32_e64 v97, v93, v31, s[100:101]
	global_store_dwordx4 v170, v[94:97], s[4:5] sc1
	v_cvt_pk_bf16_f32 v28, v82, v83
	v_cvt_pk_bf16_f32 v29, v84, v85
	v_cndmask_b32_e64 v82, v28, v32, s[100:101]
	v_cndmask_b32_e64 v83, v29, v33, s[100:101]
	s_nop 1
	v_mov_b32_dpp v84, v82 quad_perm:[1,0,3,2] row_mask:0xf bank_mask:0xf
	v_mov_b32_dpp v85, v83 quad_perm:[1,0,3,2] row_mask:0xf bank_mask:0xf
	v_cndmask_b32_e64 v86, v32, v84, s[100:101]
	v_cndmask_b32_e64 v87, v33, v85, s[100:101]
	v_cndmask_b32_e64 v88, v84, v28, s[100:101]
	v_cndmask_b32_e64 v89, v85, v29, s[100:101]
	global_store_dwordx4 v170, v[86:89], s[4:5] offset:1024 sc1
	s_and_saveexec_b64 s[18:19], vcc
	s_waitcnt lgkmcnt(0)
	v_add_f32_e32 v26, v26, v27
	v_min_f32_e32 v26, 0x49742400, v26
	v_fma_f32 v26, v26, s40, 0.5
	v_cvt_u32_f32_e32 v26, v26
	global_store_dword v0, v26, s[12:13]
	s_or_b64 exec, exec, s[18:19]
	s_add_u32 s4, s4, s10
	s_addc_u32 s5, s5, s11
	s_add_u32 s12, s12, s14
	s_addc_u32 s13, s13, s15
	s_waitcnt vmcnt(24)
	v_mul_f32_e32 v26, v111, v111
	v_mul_f32_e32 v27, v113, v113
	v_mul_f32_e32 v28, v107, v107
	v_mul_f32_e32 v29, v109, v109
	v_mul_f32_e32 v30, v103, v103
	v_mul_f32_e32 v31, v105, v105
	v_fmac_f32_e32 v26, v110, v110
	v_fmac_f32_e32 v27, v112, v112
	v_fmac_f32_e32 v28, v106, v106
	v_fmac_f32_e32 v29, v108, v108
	v_mul_f32_e32 v32, v99, v99
	v_mul_f32_e32 v33, v101, v101
	v_fmac_f32_e32 v30, v102, v102
	v_fmac_f32_e32 v31, v104, v104
	v_add_f32_e32 v26, v26, v27
	v_add_f32_e32 v27, v28, v29
	v_fmac_f32_e32 v32, v98, v98
	v_fmac_f32_e32 v33, v100, v100
	v_add_f32_e32 v28, v30, v31
	v_add_f32_e32 v26, v26, v27
	v_add_f32_e32 v26, v26, v28
	v_add_f32_e32 v27, v32, v33
	v_add_f32_e32 v26, v26, v27
	ds_bpermute_b32 v27, v1, v26
	s_waitcnt lgkmcnt(0)
	v_add_f32_e32 v26, v26, v27
	ds_bpermute_b32 v27, v20, v26
	s_waitcnt lgkmcnt(0)
	v_add_f32_e32 v26, v26, v27
	ds_bpermute_b32 v27, v21, v26
	s_waitcnt lgkmcnt(0)
	v_add_f32_e32 v26, v26, v27
	ds_bpermute_b32 v27, v22, v26
	s_waitcnt lgkmcnt(0)
	v_add_f32_e32 v26, v26, v27
	ds_bpermute_b32 v27, v23, v26
	s_waitcnt lgkmcnt(0)
	v_add_f32_e32 v26, v26, v27
	ds_bpermute_b32 v27, v24, v26
	v_cvt_pk_bf16_f32 v28, v110, v111
	v_cvt_pk_bf16_f32 v29, v112, v113
	v_cvt_pk_bf16_f32 v30, v106, v107
	v_cvt_pk_bf16_f32 v31, v108, v109
	v_cndmask_b32_e64 v106, v30, v28, s[100:101]
	v_cndmask_b32_e64 v107, v31, v29, s[100:101]
	v_cvt_pk_bf16_f32 v32, v102, v103
	v_cvt_pk_bf16_f32 v33, v104, v105
	v_mov_b32_dpp v108, v106 quad_perm:[1,0,3,2] row_mask:0xf bank_mask:0xf
	v_mov_b32_dpp v109, v107 quad_perm:[1,0,3,2] row_mask:0xf bank_mask:0xf
	v_cndmask_b32_e64 v110, v28, v108, s[100:101]
	v_cndmask_b32_e64 v111, v29, v109, s[100:101]
	v_cndmask_b32_e64 v112, v108, v30, s[100:101]
	v_cndmask_b32_e64 v113, v109, v31, s[100:101]
	global_store_dwordx4 v170, v[110:113], s[4:5] sc1
	v_cvt_pk_bf16_f32 v28, v98, v99
	v_cvt_pk_bf16_f32 v29, v100, v101
	v_cndmask_b32_e64 v98, v28, v32, s[100:101]
	v_cndmask_b32_e64 v99, v29, v33, s[100:101]
	s_nop 1
	v_mov_b32_dpp v100, v98 quad_perm:[1,0,3,2] row_mask:0xf bank_mask:0xf
	v_mov_b32_dpp v101, v99 quad_perm:[1,0,3,2] row_mask:0xf bank_mask:0xf
	v_cndmask_b32_e64 v102, v32, v100, s[100:101]
	v_cndmask_b32_e64 v103, v33, v101, s[100:101]
	v_cndmask_b32_e64 v104, v100, v28, s[100:101]
	v_cndmask_b32_e64 v105, v101, v29, s[100:101]
	global_store_dwordx4 v170, v[102:105], s[4:5] offset:1024 sc1
	s_and_saveexec_b64 s[18:19], vcc
	s_waitcnt lgkmcnt(0)
	v_add_f32_e32 v26, v26, v27
	v_min_f32_e32 v26, 0x49742400, v26
	v_fma_f32 v26, v26, s40, 0.5
	v_cvt_u32_f32_e32 v26, v26
	global_store_dword v0, v26, s[12:13]
	s_or_b64 exec, exec, s[18:19]
	s_add_u32 s4, s4, s10
	s_addc_u32 s5, s5, s11
	s_add_u32 s12, s12, s14
	s_addc_u32 s13, s13, s15
	s_waitcnt vmcnt(23)
	v_mul_f32_e32 v26, v127, v127
	v_mul_f32_e32 v27, v129, v129
	v_mul_f32_e32 v28, v123, v123
	v_mul_f32_e32 v29, v125, v125
	v_mul_f32_e32 v30, v119, v119
	v_mul_f32_e32 v31, v121, v121
	v_fmac_f32_e32 v26, v126, v126
	v_fmac_f32_e32 v27, v128, v128
	v_fmac_f32_e32 v28, v122, v122
	v_fmac_f32_e32 v29, v124, v124
	v_mul_f32_e32 v32, v115, v115
	v_mul_f32_e32 v33, v117, v117
	v_fmac_f32_e32 v30, v118, v118
	v_fmac_f32_e32 v31, v120, v120
	v_add_f32_e32 v26, v26, v27
	v_add_f32_e32 v27, v28, v29
	v_fmac_f32_e32 v32, v114, v114
	v_fmac_f32_e32 v33, v116, v116
	v_add_f32_e32 v28, v30, v31
	v_add_f32_e32 v26, v26, v27
	v_add_f32_e32 v26, v26, v28
	v_add_f32_e32 v27, v32, v33
	v_add_f32_e32 v26, v26, v27
	ds_bpermute_b32 v27, v1, v26
	s_waitcnt lgkmcnt(0)
	v_add_f32_e32 v26, v26, v27
	ds_bpermute_b32 v27, v20, v26
	s_waitcnt lgkmcnt(0)
	v_add_f32_e32 v26, v26, v27
	ds_bpermute_b32 v27, v21, v26
	s_waitcnt lgkmcnt(0)
	v_add_f32_e32 v26, v26, v27
	ds_bpermute_b32 v27, v22, v26
	s_waitcnt lgkmcnt(0)
	v_add_f32_e32 v26, v26, v27
	ds_bpermute_b32 v27, v23, v26
	s_waitcnt lgkmcnt(0)
	v_add_f32_e32 v26, v26, v27
	ds_bpermute_b32 v27, v24, v26
	v_cvt_pk_bf16_f32 v28, v126, v127
	v_cvt_pk_bf16_f32 v29, v128, v129
	v_cvt_pk_bf16_f32 v30, v122, v123
	v_cvt_pk_bf16_f32 v31, v124, v125
	v_cndmask_b32_e64 v122, v30, v28, s[100:101]
	v_cndmask_b32_e64 v123, v31, v29, s[100:101]
	v_cvt_pk_bf16_f32 v32, v118, v119
	v_cvt_pk_bf16_f32 v33, v120, v121
	v_mov_b32_dpp v124, v122 quad_perm:[1,0,3,2] row_mask:0xf bank_mask:0xf
	v_mov_b32_dpp v125, v123 quad_perm:[1,0,3,2] row_mask:0xf bank_mask:0xf
	v_cndmask_b32_e64 v126, v28, v124, s[100:101]
	v_cndmask_b32_e64 v127, v29, v125, s[100:101]
	v_cndmask_b32_e64 v128, v124, v30, s[100:101]
	v_cndmask_b32_e64 v129, v125, v31, s[100:101]
	global_store_dwordx4 v170, v[126:129], s[4:5] sc1
	v_cvt_pk_bf16_f32 v28, v114, v115
	v_cvt_pk_bf16_f32 v29, v116, v117
	v_cndmask_b32_e64 v114, v28, v32, s[100:101]
	v_cndmask_b32_e64 v115, v29, v33, s[100:101]
	s_nop 1
	v_mov_b32_dpp v116, v114 quad_perm:[1,0,3,2] row_mask:0xf bank_mask:0xf
	v_mov_b32_dpp v117, v115 quad_perm:[1,0,3,2] row_mask:0xf bank_mask:0xf
	v_cndmask_b32_e64 v118, v32, v116, s[100:101]
	v_cndmask_b32_e64 v119, v33, v117, s[100:101]
	v_cndmask_b32_e64 v120, v116, v28, s[100:101]
	v_cndmask_b32_e64 v121, v117, v29, s[100:101]
	global_store_dwordx4 v170, v[118:121], s[4:5] offset:1024 sc1
	s_and_saveexec_b64 s[18:19], vcc
	s_waitcnt lgkmcnt(0)
	v_add_f32_e32 v26, v26, v27
	v_min_f32_e32 v26, 0x49742400, v26
	v_fma_f32 v26, v26, s40, 0.5
	v_cvt_u32_f32_e32 v26, v26
	global_store_dword v0, v26, s[12:13]
	s_or_b64 exec, exec, s[18:19]
	s_add_u32 s4, s4, s10
	s_addc_u32 s5, s5, s11
	s_add_u32 s12, s12, s14
	s_addc_u32 s13, s13, s15
	s_waitcnt vmcnt(22)
	v_mul_f32_e32 v26, v143, v143
	v_mul_f32_e32 v27, v145, v145
	v_mul_f32_e32 v28, v139, v139
	v_mul_f32_e32 v29, v141, v141
	v_mul_f32_e32 v30, v135, v135
	v_mul_f32_e32 v31, v137, v137
	v_fmac_f32_e32 v26, v142, v142
	v_fmac_f32_e32 v27, v144, v144
	v_fmac_f32_e32 v28, v138, v138
	v_fmac_f32_e32 v29, v140, v140
	v_mul_f32_e32 v32, v131, v131
	v_mul_f32_e32 v33, v133, v133
	v_fmac_f32_e32 v30, v134, v134
	v_fmac_f32_e32 v31, v136, v136
	v_add_f32_e32 v26, v26, v27
	v_add_f32_e32 v27, v28, v29
	v_fmac_f32_e32 v32, v130, v130
	v_fmac_f32_e32 v33, v132, v132
	v_add_f32_e32 v28, v30, v31
	v_add_f32_e32 v26, v26, v27
	v_add_f32_e32 v26, v26, v28
	v_add_f32_e32 v27, v32, v33
	v_add_f32_e32 v26, v26, v27
	ds_bpermute_b32 v27, v1, v26
	s_waitcnt lgkmcnt(0)
	v_add_f32_e32 v26, v26, v27
	ds_bpermute_b32 v27, v20, v26
	s_waitcnt lgkmcnt(0)
	v_add_f32_e32 v26, v26, v27
	ds_bpermute_b32 v27, v21, v26
	s_waitcnt lgkmcnt(0)
	v_add_f32_e32 v26, v26, v27
	ds_bpermute_b32 v27, v22, v26
	s_waitcnt lgkmcnt(0)
	v_add_f32_e32 v26, v26, v27
	ds_bpermute_b32 v27, v23, v26
	s_waitcnt lgkmcnt(0)
	v_add_f32_e32 v26, v26, v27
	ds_bpermute_b32 v27, v24, v26
	v_cvt_pk_bf16_f32 v28, v142, v143
	v_cvt_pk_bf16_f32 v29, v144, v145
	v_cvt_pk_bf16_f32 v30, v138, v139
	v_cvt_pk_bf16_f32 v31, v140, v141
	v_cndmask_b32_e64 v138, v30, v28, s[100:101]
	v_cndmask_b32_e64 v139, v31, v29, s[100:101]
	v_cvt_pk_bf16_f32 v32, v134, v135
	v_cvt_pk_bf16_f32 v33, v136, v137
	v_mov_b32_dpp v140, v138 quad_perm:[1,0,3,2] row_mask:0xf bank_mask:0xf
	v_mov_b32_dpp v141, v139 quad_perm:[1,0,3,2] row_mask:0xf bank_mask:0xf
	v_cndmask_b32_e64 v142, v28, v140, s[100:101]
	v_cndmask_b32_e64 v143, v29, v141, s[100:101]
	v_cndmask_b32_e64 v144, v140, v30, s[100:101]
	v_cndmask_b32_e64 v145, v141, v31, s[100:101]
	global_store_dwordx4 v170, v[142:145], s[4:5] sc1
	v_cvt_pk_bf16_f32 v28, v130, v131
	v_cvt_pk_bf16_f32 v29, v132, v133
	v_cndmask_b32_e64 v130, v28, v32, s[100:101]
	v_cndmask_b32_e64 v131, v29, v33, s[100:101]
	s_nop 1
	v_mov_b32_dpp v132, v130 quad_perm:[1,0,3,2] row_mask:0xf bank_mask:0xf
	v_mov_b32_dpp v133, v131 quad_perm:[1,0,3,2] row_mask:0xf bank_mask:0xf
	v_cndmask_b32_e64 v134, v32, v132, s[100:101]
	v_cndmask_b32_e64 v135, v33, v133, s[100:101]
	v_cndmask_b32_e64 v136, v132, v28, s[100:101]
	v_cndmask_b32_e64 v137, v133, v29, s[100:101]
	global_store_dwordx4 v170, v[134:137], s[4:5] offset:1024 sc1
	s_and_saveexec_b64 s[18:19], vcc
	s_waitcnt lgkmcnt(0)
	v_add_f32_e32 v26, v26, v27
	v_min_f32_e32 v26, 0x49742400, v26
	v_fma_f32 v26, v26, s40, 0.5
	v_cvt_u32_f32_e32 v26, v26
	global_store_dword v0, v26, s[12:13]
	s_or_b64 exec, exec, s[18:19]
	s_add_u32 s4, s4, s10
	s_addc_u32 s5, s5, s11
	s_add_u32 s12, s12, s14
	s_addc_u32 s13, s13, s15
	s_waitcnt vmcnt(21)
	v_mul_f32_e32 v26, v159, v159
	v_mul_f32_e32 v27, v161, v161
	v_mul_f32_e32 v28, v155, v155
	v_mul_f32_e32 v29, v157, v157
	v_mul_f32_e32 v30, v151, v151
	v_mul_f32_e32 v31, v153, v153
	v_fmac_f32_e32 v26, v158, v158
	v_fmac_f32_e32 v27, v160, v160
	v_fmac_f32_e32 v28, v154, v154
	v_fmac_f32_e32 v29, v156, v156
	v_mul_f32_e32 v32, v147, v147
	v_mul_f32_e32 v33, v149, v149
	v_fmac_f32_e32 v30, v150, v150
	v_fmac_f32_e32 v31, v152, v152
	v_add_f32_e32 v26, v26, v27
	v_add_f32_e32 v27, v28, v29
	v_fmac_f32_e32 v32, v146, v146
	v_fmac_f32_e32 v33, v148, v148
	v_add_f32_e32 v28, v30, v31
	v_add_f32_e32 v26, v26, v27
	v_add_f32_e32 v26, v26, v28
	v_add_f32_e32 v27, v32, v33
	v_add_f32_e32 v26, v26, v27
	ds_bpermute_b32 v27, v1, v26
	s_waitcnt lgkmcnt(0)
	v_add_f32_e32 v26, v26, v27
	ds_bpermute_b32 v27, v20, v26
	s_waitcnt lgkmcnt(0)
	v_add_f32_e32 v26, v26, v27
	ds_bpermute_b32 v27, v21, v26
	s_waitcnt lgkmcnt(0)
	v_add_f32_e32 v26, v26, v27
	ds_bpermute_b32 v27, v22, v26
	s_waitcnt lgkmcnt(0)
	v_add_f32_e32 v26, v26, v27
	ds_bpermute_b32 v27, v23, v26
	s_waitcnt lgkmcnt(0)
	v_add_f32_e32 v26, v26, v27
	ds_bpermute_b32 v27, v24, v26
	v_cvt_pk_bf16_f32 v28, v158, v159
	v_cvt_pk_bf16_f32 v29, v160, v161
	v_cvt_pk_bf16_f32 v30, v154, v155
	v_cvt_pk_bf16_f32 v31, v156, v157
	v_cndmask_b32_e64 v154, v30, v28, s[100:101]
	v_cndmask_b32_e64 v155, v31, v29, s[100:101]
	v_cvt_pk_bf16_f32 v32, v150, v151
	v_cvt_pk_bf16_f32 v33, v152, v153
	v_mov_b32_dpp v156, v154 quad_perm:[1,0,3,2] row_mask:0xf bank_mask:0xf
	v_mov_b32_dpp v157, v155 quad_perm:[1,0,3,2] row_mask:0xf bank_mask:0xf
	v_cndmask_b32_e64 v158, v28, v156, s[100:101]
	v_cndmask_b32_e64 v159, v29, v157, s[100:101]
	v_cndmask_b32_e64 v160, v156, v30, s[100:101]
	v_cndmask_b32_e64 v161, v157, v31, s[100:101]
	global_store_dwordx4 v170, v[158:161], s[4:5] sc1
	v_cvt_pk_bf16_f32 v28, v146, v147
	v_cvt_pk_bf16_f32 v29, v148, v149
	v_cndmask_b32_e64 v146, v28, v32, s[100:101]
	v_cndmask_b32_e64 v147, v29, v33, s[100:101]
	s_nop 1
	v_mov_b32_dpp v148, v146 quad_perm:[1,0,3,2] row_mask:0xf bank_mask:0xf
	v_mov_b32_dpp v149, v147 quad_perm:[1,0,3,2] row_mask:0xf bank_mask:0xf
	v_cndmask_b32_e64 v150, v32, v148, s[100:101]
	v_cndmask_b32_e64 v151, v33, v149, s[100:101]
	v_cndmask_b32_e64 v152, v148, v28, s[100:101]
	v_cndmask_b32_e64 v153, v149, v29, s[100:101]
	global_store_dwordx4 v170, v[150:153], s[4:5] offset:1024 sc1
	s_and_saveexec_b64 s[18:19], vcc
	s_waitcnt lgkmcnt(0)
	v_add_f32_e32 v26, v26, v27
	v_min_f32_e32 v26, 0x49742400, v26
	v_fma_f32 v26, v26, s40, 0.5
	v_cvt_u32_f32_e32 v26, v26
	global_store_dword v0, v26, s[12:13]
	s_or_b64 exec, exec, s[18:19]
	s_branch .LBB0_676
